# adds: k/v window copy of batches 40..127 moved to the workgroups that idle at the end of the down-projection phase; out-projection phase keeps batches 0..39
# baseline (speedup 1.0000x reference)
; __device__ __forceinline__ void kvwin_copy(const Frame& F, int gt, int GT) {
;     const int per = 124 * 64;
;     for (int i0 = gt; i0 < NB * per; i0 += 4 * GT) { f32x4 a[4], b[4]; size_t so[4], dof[4];
; #pragma unroll
;         for (int u = 0; u < 4; ++u) { const int i = i0 + u * GT; const int ii = i < NB * per ? i : 0; const int bb = ii / per, o = ii - bb * per; so[u] = (size_t)bb * 8192 + 256 + o; dof[u] = (size_t)bb * 8192 + o;
;             a[u] = __builtin_nontemporal_load((const f32x4*)F.in[2] + so[u]); b[u] = __builtin_nontemporal_load((const f32x4*)F.in[3] + so[u]); }
; #pragma unroll
;         for (int u = 0; u < 4; ++u) { if (i0 + u * GT < NB * per) { __builtin_nontemporal_store(a[u], (f32x4*)(F.out + O_KWS) + dof[u]); __builtin_nontemporal_store(b[u], (f32x4*)(F.out + O_VWS) + dof[u]); } } }
; }
; __global__ void __launch_bounds__(512, 2) fwd_mega(Params prm) {
;     ...
;         if (F.G == 256) { if (F.bid >= 64) kvwin_copy(F, (F.bid - 64) * 512 + F.tid, (F.G - 64) * 512); } else kvwin_copy(F, F.bid * 512 + F.tid, F.G * 512); }
.LBB0_901:
	s_cmp_lt_i32 s33, 64
	s_cbranch_scc1 .LBB0_912
	s_lshl_b32 s0, s33, 9
	s_addk_i32 s0, 0x8000
	v_add_u32_e32 v38, s0, v144
	s_mov_b32 s0, 0x4d800
	v_cmp_gt_i32_e32 vcc, s0, v38
	s_and_saveexec_b64 s[6:7], vcc
	s_cbranch_execz .LBB0_911
	v_readlane_b32 s8, v245, 21
	v_readlane_b32 s14, v245, 27
	v_readlane_b32 s15, v245, 28
	v_readlane_b32 s22, v245, 35
	v_readlane_b32 s23, v245, 36
	s_mov_b64 s[14:15], s[22:23]
	v_readlane_b32 s9, v245, 22
	s_add_u32 s8, s14, 0x4541010
	v_readlane_b32 s10, v245, 23
	s_addc_u32 s9, s15, 0
	v_readlane_b32 s11, v245, 24
	v_readlane_b32 s12, v245, 25
	v_readlane_b32 s13, v245, 26
	v_readlane_b32 s18, v245, 31
	v_readlane_b32 s19, v245, 32
	v_readlane_b32 s20, v245, 33
	v_readlane_b32 s21, v245, 34
	s_add_u32 s10, s14, 0x5541010
	s_addc_u32 s11, s15, 0
	s_mov_b64 s[12:13], 0
	s_mov_b32 s18, 0x35800
	s_mov_b32 s19, 0x84210843
	s_movk_i32 s20, 0xe100
	s_mov_b64 s[14:15], 0x1000
	s_waitcnt vmcnt(0)
	v_mov_b64_e32 v[24:25], 0x1000
	s_mov_b32 s21, 0x1d800
	s_mov_b32 s22, 0x5800
	s_mov_b32 s23, 0xfffed7ff
	v_readlane_b32 s16, v245, 29
	v_readlane_b32 s17, v245, 30
	s_branch .LBB0_905

; __device__ __forceinline__ void kvwin_copy(const Frame& F, int gt, int GT) {
;     const int per = 124 * 64;
;     for (int i0 = gt; i0 < NB * per; i0 += 4 * GT) { f32x4 a[4], b[4]; size_t so[4], dof[4];
; #pragma unroll
;         for (int u = 0; u < 4; ++u) { const int i = i0 + u * GT; const int ii = i < NB * per ? i : 0; const int bb = ii / per, o = ii - bb * per; so[u] = (size_t)bb * 8192 + 256 + o; dof[u] = (size_t)bb * 8192 + o;
;             a[u] = __builtin_nontemporal_load((const f32x4*)F.in[2] + so[u]); b[u] = __builtin_nontemporal_load((const f32x4*)F.in[3] + so[u]); }
.LBB0_1187:
	s_waitcnt vmcnt(0)
	v_readlane_b32 s36, v245, 21
	v_readlane_b32 s50, v245, 35
	v_readlane_b32 s51, v245, 36
	s_mov_b32 s80, s92
	s_mov_b32 s81, s93
	s_barrier
	v_readlane_b32 s37, v245, 22
	v_readlane_b32 s38, v245, 23
	v_readlane_b32 s39, v245, 24
	v_readlane_b32 s40, v245, 25
	v_readlane_b32 s41, v245, 26
	v_readlane_b32 s42, v245, 27
	v_readlane_b32 s43, v245, 28
	v_readlane_b32 s44, v245, 29
	v_readlane_b32 s45, v245, 30
	v_readlane_b32 s46, v245, 31
	v_readlane_b32 s47, v245, 32
	v_readlane_b32 s48, v245, 33
	v_readlane_b32 s49, v245, 34
	s_cmpk_lt_i32 s33, 176
	s_cbranch_scc1 .Lmy_kv_end
	s_load_dwordx4 s[8:11], s[98:99], 0x10
	s_load_dwordx2 s[16:17], s[98:99], 0xb8
	s_sub_i32 s20, s33, 176
	s_lshl_b32 s20, s20, 9
	s_add_i32 s20, s20, 0x50000
	v_mbcnt_lo_u32_b32 v104, -1, 0
	v_mbcnt_hi_u32_b32 v104, -1, v104
	s_lshl_b32 s22, s80, 6
	s_add_i32 s20, s20, s22
	v_add_u32_e32 v104, s20, v104
	s_mov_b32 s21, 0x100000
	s_waitcnt lgkmcnt(0)
	s_add_u32 s8, s8, 0x1000
	s_addc_u32 s9, s9, 0
	s_add_u32 s10, s10, 0x1000
	s_addc_u32 s11, s11, 0
	s_add_u32 s12, s16, 0x4541010
	s_addc_u32 s13, s17, 0
	s_add_u32 s14, s16, 0x5541010
	s_addc_u32 s15, s17, 0
	v_add_u32_e32 v105, 0x0, v104
	v_and_b32_e32 v106, 0x1fff, v105
	v_cmp_gt_u32_e32 vcc, 0x1f00, v106
	v_cmp_gt_u32_e64 s[18:19], s21, v105
	s_and_b64 vcc, vcc, s[18:19]
	v_lshlrev_b32_e32 v107, 4, v105
	s_and_saveexec_b64 s[18:19], vcc
	global_load_dwordx4 v[32:35], v107, s[8:9] nt
	global_load_dwordx4 v[36:39], v107, s[10:11] nt
	s_mov_b64 exec, s[18:19]
	v_add_u32_e32 v105, 0xa000, v104
	v_and_b32_e32 v106, 0x1fff, v105
	v_cmp_gt_u32_e32 vcc, 0x1f00, v106
	v_cmp_gt_u32_e64 s[18:19], s21, v105
	s_and_b64 vcc, vcc, s[18:19]
	v_lshlrev_b32_e32 v108, 4, v105
	s_and_saveexec_b64 s[18:19], vcc
	global_load_dwordx4 v[40:43], v108, s[8:9] nt
	global_load_dwordx4 v[44:47], v108, s[10:11] nt
	s_mov_b64 exec, s[18:19]
	v_add_u32_e32 v105, 0x14000, v104
	v_and_b32_e32 v106, 0x1fff, v105
	v_cmp_gt_u32_e32 vcc, 0x1f00, v106
	v_cmp_gt_u32_e64 s[18:19], s21, v105
	s_and_b64 vcc, vcc, s[18:19]
	v_lshlrev_b32_e32 v109, 4, v105
	s_and_saveexec_b64 s[18:19], vcc
	global_load_dwordx4 v[48:51], v109, s[8:9] nt
	global_load_dwordx4 v[52:55], v109, s[10:11] nt
	s_mov_b64 exec, s[18:19]
	v_add_u32_e32 v105, 0x1e000, v104
	v_and_b32_e32 v106, 0x1fff, v105
	v_cmp_gt_u32_e32 vcc, 0x1f00, v106
	v_cmp_gt_u32_e64 s[18:19], s21, v105
	s_and_b64 vcc, vcc, s[18:19]
	v_lshlrev_b32_e32 v110, 4, v105
	s_and_saveexec_b64 s[18:19], vcc
	global_load_dwordx4 v[56:59], v110, s[8:9] nt
	global_load_dwordx4 v[60:63], v110, s[10:11] nt
	s_mov_b64 exec, s[18:19]
	v_add_u32_e32 v105, 0x28000, v104
	v_and_b32_e32 v106, 0x1fff, v105
	v_cmp_gt_u32_e32 vcc, 0x1f00, v106
	v_cmp_gt_u32_e64 s[18:19], s21, v105
	s_and_b64 vcc, vcc, s[18:19]
	v_lshlrev_b32_e32 v111, 4, v105
	s_and_saveexec_b64 s[18:19], vcc
	global_load_dwordx4 v[64:67], v111, s[8:9] nt
	global_load_dwordx4 v[68:71], v111, s[10:11] nt
	s_mov_b64 exec, s[18:19]
	v_add_u32_e32 v105, 0x32000, v104
	v_and_b32_e32 v106, 0x1fff, v105
	v_cmp_gt_u32_e32 vcc, 0x1f00, v106
	v_cmp_gt_u32_e64 s[18:19], s21, v105
	s_and_b64 vcc, vcc, s[18:19]
	v_lshlrev_b32_e32 v112, 4, v105
	s_and_saveexec_b64 s[18:19], vcc
	global_load_dwordx4 v[72:75], v112, s[8:9] nt
	global_load_dwordx4 v[76:79], v112, s[10:11] nt
	s_mov_b64 exec, s[18:19]
	v_add_u32_e32 v105, 0x3c000, v104
	v_and_b32_e32 v106, 0x1fff, v105
	v_cmp_gt_u32_e32 vcc, 0x1f00, v106
	v_cmp_gt_u32_e64 s[18:19], s21, v105
	s_and_b64 vcc, vcc, s[18:19]
	v_lshlrev_b32_e32 v113, 4, v105
	s_and_saveexec_b64 s[18:19], vcc
	global_load_dwordx4 v[80:83], v113, s[8:9] nt
	global_load_dwordx4 v[84:87], v113, s[10:11] nt
	s_mov_b64 exec, s[18:19]
	v_add_u32_e32 v105, 0x46000, v104
	v_and_b32_e32 v106, 0x1fff, v105
	v_cmp_gt_u32_e32 vcc, 0x1f00, v106
	v_cmp_gt_u32_e64 s[18:19], s21, v105
	s_and_b64 vcc, vcc, s[18:19]
	v_lshlrev_b32_e32 v114, 4, v105
	s_and_saveexec_b64 s[18:19], vcc
	global_load_dwordx4 v[88:91], v114, s[8:9] nt
	global_load_dwordx4 v[92:95], v114, s[10:11] nt
	s_mov_b64 exec, s[18:19]
	v_add_u32_e32 v105, 0x50000, v104
	v_and_b32_e32 v106, 0x1fff, v105
	v_cmp_gt_u32_e32 vcc, 0x1f00, v106
	v_cmp_gt_u32_e64 s[18:19], s21, v105
	s_and_b64 vcc, vcc, s[18:19]
	v_lshlrev_b32_e32 v115, 4, v105
	s_and_saveexec_b64 s[18:19], vcc
	global_load_dwordx4 v[96:99], v115, s[8:9] nt
	global_load_dwordx4 v[100:103], v115, s[10:11] nt
	s_mov_b64 exec, s[18:19]
	s_waitcnt vmcnt(0)
; __device__ __forceinline__ void kvwin_copy(const Frame& F, int gt, int GT) {
;     ...
;         for (int u = 0; u < 4; ++u) { const int i = i0 + u * GT; const int ii = i < NB * per ? i : 0; const int bb = ii / per, o = ii - bb * per; so[u] = (size_t)bb * 8192 + 256 + o; dof[u] = (size_t)bb * 8192 + o;
;             a[u] = __builtin_nontemporal_load((const f32x4*)F.in[2] + so[u]); b[u] = __builtin_nontemporal_load((const f32x4*)F.in[3] + so[u]); }
; #pragma unroll
;         for (int u = 0; u < 4; ++u) { if (i0 + u * GT < NB * per) { __builtin_nontemporal_store(a[u], (f32x4*)(F.out + O_KWS) + dof[u]); __builtin_nontemporal_store(b[u], (f32x4*)(F.out + O_VWS) + dof[u]); } } }
	v_add_u32_e32 v105, 0x0, v104
	v_and_b32_e32 v106, 0x1fff, v105
	v_cmp_gt_u32_e32 vcc, 0x1f00, v106
	v_cmp_gt_u32_e64 s[18:19], s21, v105
	s_and_b64 vcc, vcc, s[18:19]
	v_lshlrev_b32_e32 v107, 4, v105
	s_and_saveexec_b64 s[18:19], vcc
	global_store_dwordx4 v107, v[32:35], s[12:13] nt
	global_store_dwordx4 v107, v[36:39], s[14:15] nt
	s_mov_b64 exec, s[18:19]
	v_add_u32_e32 v105, 0xa000, v104
	v_and_b32_e32 v106, 0x1fff, v105
	v_cmp_gt_u32_e32 vcc, 0x1f00, v106
	v_cmp_gt_u32_e64 s[18:19], s21, v105
	s_and_b64 vcc, vcc, s[18:19]
	v_lshlrev_b32_e32 v108, 4, v105
	s_and_saveexec_b64 s[18:19], vcc
	global_store_dwordx4 v108, v[40:43], s[12:13] nt
	global_store_dwordx4 v108, v[44:47], s[14:15] nt
	s_mov_b64 exec, s[18:19]
	v_add_u32_e32 v105, 0x14000, v104
	v_and_b32_e32 v106, 0x1fff, v105
	v_cmp_gt_u32_e32 vcc, 0x1f00, v106
	v_cmp_gt_u32_e64 s[18:19], s21, v105
	s_and_b64 vcc, vcc, s[18:19]
	v_lshlrev_b32_e32 v109, 4, v105
	s_and_saveexec_b64 s[18:19], vcc
	global_store_dwordx4 v109, v[48:51], s[12:13] nt
	global_store_dwordx4 v109, v[52:55], s[14:15] nt
	s_mov_b64 exec, s[18:19]
	v_add_u32_e32 v105, 0x1e000, v104
	v_and_b32_e32 v106, 0x1fff, v105
	v_cmp_gt_u32_e32 vcc, 0x1f00, v106
	v_cmp_gt_u32_e64 s[18:19], s21, v105
	s_and_b64 vcc, vcc, s[18:19]
	v_lshlrev_b32_e32 v110, 4, v105
	s_and_saveexec_b64 s[18:19], vcc
	global_store_dwordx4 v110, v[56:59], s[12:13] nt
	global_store_dwordx4 v110, v[60:63], s[14:15] nt
	s_mov_b64 exec, s[18:19]
	v_add_u32_e32 v105, 0x28000, v104
	v_and_b32_e32 v106, 0x1fff, v105
	v_cmp_gt_u32_e32 vcc, 0x1f00, v106
	v_cmp_gt_u32_e64 s[18:19], s21, v105
	s_and_b64 vcc, vcc, s[18:19]
	v_lshlrev_b32_e32 v111, 4, v105
	s_and_saveexec_b64 s[18:19], vcc
	global_store_dwordx4 v111, v[64:67], s[12:13] nt
	global_store_dwordx4 v111, v[68:71], s[14:15] nt
	s_mov_b64 exec, s[18:19]
	v_add_u32_e32 v105, 0x32000, v104
	v_and_b32_e32 v106, 0x1fff, v105
	v_cmp_gt_u32_e32 vcc, 0x1f00, v106
	v_cmp_gt_u32_e64 s[18:19], s21, v105
	s_and_b64 vcc, vcc, s[18:19]
	v_lshlrev_b32_e32 v112, 4, v105
	s_and_saveexec_b64 s[18:19], vcc
	global_store_dwordx4 v112, v[72:75], s[12:13] nt
	global_store_dwordx4 v112, v[76:79], s[14:15] nt
	s_mov_b64 exec, s[18:19]
	v_add_u32_e32 v105, 0x3c000, v104
	v_and_b32_e32 v106, 0x1fff, v105
	v_cmp_gt_u32_e32 vcc, 0x1f00, v106
	v_cmp_gt_u32_e64 s[18:19], s21, v105
	s_and_b64 vcc, vcc, s[18:19]
	v_lshlrev_b32_e32 v113, 4, v105
	s_and_saveexec_b64 s[18:19], vcc
	global_store_dwordx4 v113, v[80:83], s[12:13] nt
	global_store_dwordx4 v113, v[84:87], s[14:15] nt
	s_mov_b64 exec, s[18:19]
	v_add_u32_e32 v105, 0x46000, v104
	v_and_b32_e32 v106, 0x1fff, v105
	v_cmp_gt_u32_e32 vcc, 0x1f00, v106
	v_cmp_gt_u32_e64 s[18:19], s21, v105
	s_and_b64 vcc, vcc, s[18:19]
	v_lshlrev_b32_e32 v114, 4, v105
	s_and_saveexec_b64 s[18:19], vcc
	global_store_dwordx4 v114, v[88:91], s[12:13] nt
	global_store_dwordx4 v114, v[92:95], s[14:15] nt
	s_mov_b64 exec, s[18:19]
	v_add_u32_e32 v105, 0x50000, v104
	v_and_b32_e32 v106, 0x1fff, v105
	v_cmp_gt_u32_e32 vcc, 0x1f00, v106
	v_cmp_gt_u32_e64 s[18:19], s21, v105
	s_and_b64 vcc, vcc, s[18:19]
	v_lshlrev_b32_e32 v115, 4, v105
	s_and_saveexec_b64 s[18:19], vcc
	global_store_dwordx4 v115, v[96:99], s[12:13] nt
	global_store_dwordx4 v115, v[100:103], s[14:15] nt
	s_mov_b64 exec, s[18:19]
	v_add_u32_e32 v105, 0x5a000, v104
	v_and_b32_e32 v106, 0x1fff, v105
	v_cmp_gt_u32_e32 vcc, 0x1f00, v106
	v_cmp_gt_u32_e64 s[18:19], s21, v105
	s_and_b64 vcc, vcc, s[18:19]
	v_lshlrev_b32_e32 v107, 4, v105
	s_and_saveexec_b64 s[18:19], vcc
	global_load_dwordx4 v[32:35], v107, s[8:9] nt
	global_load_dwordx4 v[36:39], v107, s[10:11] nt
	s_mov_b64 exec, s[18:19]
	v_add_u32_e32 v105, 0x64000, v104
	v_and_b32_e32 v106, 0x1fff, v105
	v_cmp_gt_u32_e32 vcc, 0x1f00, v106
	v_cmp_gt_u32_e64 s[18:19], s21, v105
	s_and_b64 vcc, vcc, s[18:19]
	v_lshlrev_b32_e32 v108, 4, v105
	s_and_saveexec_b64 s[18:19], vcc
	global_load_dwordx4 v[40:43], v108, s[8:9] nt
	global_load_dwordx4 v[44:47], v108, s[10:11] nt
	s_mov_b64 exec, s[18:19]
	v_add_u32_e32 v105, 0x6e000, v104
	v_and_b32_e32 v106, 0x1fff, v105
	v_cmp_gt_u32_e32 vcc, 0x1f00, v106
	v_cmp_gt_u32_e64 s[18:19], s21, v105
	s_and_b64 vcc, vcc, s[18:19]
	v_lshlrev_b32_e32 v109, 4, v105
	s_and_saveexec_b64 s[18:19], vcc
	global_load_dwordx4 v[48:51], v109, s[8:9] nt
	global_load_dwordx4 v[52:55], v109, s[10:11] nt
	s_mov_b64 exec, s[18:19]
	v_add_u32_e32 v105, 0x78000, v104
	v_and_b32_e32 v106, 0x1fff, v105
	v_cmp_gt_u32_e32 vcc, 0x1f00, v106
	v_cmp_gt_u32_e64 s[18:19], s21, v105
	s_and_b64 vcc, vcc, s[18:19]
	v_lshlrev_b32_e32 v110, 4, v105
	s_and_saveexec_b64 s[18:19], vcc
	global_load_dwordx4 v[56:59], v110, s[8:9] nt
	global_load_dwordx4 v[60:63], v110, s[10:11] nt
	s_mov_b64 exec, s[18:19]
	v_add_u32_e32 v105, 0x82000, v104
	v_and_b32_e32 v106, 0x1fff, v105
	v_cmp_gt_u32_e32 vcc, 0x1f00, v106
	v_cmp_gt_u32_e64 s[18:19], s21, v105
	s_and_b64 vcc, vcc, s[18:19]
	v_lshlrev_b32_e32 v111, 4, v105
	s_and_saveexec_b64 s[18:19], vcc
	global_load_dwordx4 v[64:67], v111, s[8:9] nt
	global_load_dwordx4 v[68:71], v111, s[10:11] nt
	s_mov_b64 exec, s[18:19]
	v_add_u32_e32 v105, 0x8c000, v104
	v_and_b32_e32 v106, 0x1fff, v105
	v_cmp_gt_u32_e32 vcc, 0x1f00, v106
	v_cmp_gt_u32_e64 s[18:19], s21, v105
	s_and_b64 vcc, vcc, s[18:19]
	v_lshlrev_b32_e32 v112, 4, v105
	s_and_saveexec_b64 s[18:19], vcc
	global_load_dwordx4 v[72:75], v112, s[8:9] nt
	global_load_dwordx4 v[76:79], v112, s[10:11] nt
	s_mov_b64 exec, s[18:19]
	v_add_u32_e32 v105, 0x96000, v104
	v_and_b32_e32 v106, 0x1fff, v105
	v_cmp_gt_u32_e32 vcc, 0x1f00, v106
	v_cmp_gt_u32_e64 s[18:19], s21, v105
	s_and_b64 vcc, vcc, s[18:19]
	v_lshlrev_b32_e32 v113, 4, v105
	s_and_saveexec_b64 s[18:19], vcc
	global_load_dwordx4 v[80:83], v113, s[8:9] nt
	global_load_dwordx4 v[84:87], v113, s[10:11] nt
	s_mov_b64 exec, s[18:19]
	v_add_u32_e32 v105, 0xa0000, v104
	v_and_b32_e32 v106, 0x1fff, v105
	v_cmp_gt_u32_e32 vcc, 0x1f00, v106
	v_cmp_gt_u32_e64 s[18:19], s21, v105
	s_and_b64 vcc, vcc, s[18:19]
	v_lshlrev_b32_e32 v114, 4, v105
	s_and_saveexec_b64 s[18:19], vcc
	global_load_dwordx4 v[88:91], v114, s[8:9] nt
	global_load_dwordx4 v[92:95], v114, s[10:11] nt
	s_mov_b64 exec, s[18:19]
	v_add_u32_e32 v105, 0xaa000, v104
	v_and_b32_e32 v106, 0x1fff, v105
	v_cmp_gt_u32_e32 vcc, 0x1f00, v106
	v_cmp_gt_u32_e64 s[18:19], s21, v105
	s_and_b64 vcc, vcc, s[18:19]
	v_lshlrev_b32_e32 v115, 4, v105
	s_and_saveexec_b64 s[18:19], vcc
	global_load_dwordx4 v[96:99], v115, s[8:9] nt
	global_load_dwordx4 v[100:103], v115, s[10:11] nt
	s_mov_b64 exec, s[18:19]
	s_waitcnt vmcnt(0)
; __device__ __forceinline__ unsigned xb_add(unsigned* p, unsigned v) { return __hip_atomic_fetch_add(p, v, __ATOMIC_RELAXED, __HIP_MEMORY_SCOPE_AGENT); }
; __device__ __forceinline__ void xcd_barrier(const XcdBarrier& b) {
;     asm volatile("s_waitcnt vmcnt(0)" ::: "memory");
;     __syncthreads();
;     if (threadIdx.x == 0) {
;         unsigned* bar = b.bar;
;         __builtin_amdgcn_s_waitcnt(0);
;         unsigned nloc = b.st[0], nx = b.st[1];
;         if (nloc == 0u) { xcd_barrier_complete(bar, b.x, nloc, nx); b.st[0] = nloc; b.st[1] = nx; }
;         const unsigned old = xb_add(&bar[XB_XSUB(b.x)], 1u);
; __device__ __forceinline__ void kvwin_copy(const Frame& F, int gt, int GT) {
;     ...
;         for (int u = 0; u < 4; ++u) { if (i0 + u * GT < NB * per) { __builtin_nontemporal_store(a[u], (f32x4*)(F.out + O_KWS) + dof[u]); __builtin_nontemporal_store(b[u], (f32x4*)(F.out + O_VWS) + dof[u]); } } }
; }
	v_add_u32_e32 v105, 0x5a000, v104
	v_and_b32_e32 v106, 0x1fff, v105
	v_cmp_gt_u32_e32 vcc, 0x1f00, v106
	v_cmp_gt_u32_e64 s[18:19], s21, v105
	s_and_b64 vcc, vcc, s[18:19]
	v_lshlrev_b32_e32 v107, 4, v105
	s_and_saveexec_b64 s[18:19], vcc
	global_store_dwordx4 v107, v[32:35], s[12:13] nt
	global_store_dwordx4 v107, v[36:39], s[14:15] nt
	s_mov_b64 exec, s[18:19]
	v_add_u32_e32 v105, 0x64000, v104
	v_and_b32_e32 v106, 0x1fff, v105
	v_cmp_gt_u32_e32 vcc, 0x1f00, v106
	v_cmp_gt_u32_e64 s[18:19], s21, v105
	s_and_b64 vcc, vcc, s[18:19]
	v_lshlrev_b32_e32 v108, 4, v105
	s_and_saveexec_b64 s[18:19], vcc
	global_store_dwordx4 v108, v[40:43], s[12:13] nt
	global_store_dwordx4 v108, v[44:47], s[14:15] nt
	s_mov_b64 exec, s[18:19]
	v_add_u32_e32 v105, 0x6e000, v104
	v_and_b32_e32 v106, 0x1fff, v105
	v_cmp_gt_u32_e32 vcc, 0x1f00, v106
	v_cmp_gt_u32_e64 s[18:19], s21, v105
	s_and_b64 vcc, vcc, s[18:19]
	v_lshlrev_b32_e32 v109, 4, v105
	s_and_saveexec_b64 s[18:19], vcc
	global_store_dwordx4 v109, v[48:51], s[12:13] nt
	global_store_dwordx4 v109, v[52:55], s[14:15] nt
	s_mov_b64 exec, s[18:19]
	v_add_u32_e32 v105, 0x78000, v104
	v_and_b32_e32 v106, 0x1fff, v105
	v_cmp_gt_u32_e32 vcc, 0x1f00, v106
	v_cmp_gt_u32_e64 s[18:19], s21, v105
	s_and_b64 vcc, vcc, s[18:19]
	v_lshlrev_b32_e32 v110, 4, v105
	s_and_saveexec_b64 s[18:19], vcc
	global_store_dwordx4 v110, v[56:59], s[12:13] nt
	global_store_dwordx4 v110, v[60:63], s[14:15] nt
	s_mov_b64 exec, s[18:19]
	v_add_u32_e32 v105, 0x82000, v104
	v_and_b32_e32 v106, 0x1fff, v105
	v_cmp_gt_u32_e32 vcc, 0x1f00, v106
	v_cmp_gt_u32_e64 s[18:19], s21, v105
	s_and_b64 vcc, vcc, s[18:19]
	v_lshlrev_b32_e32 v111, 4, v105
	s_and_saveexec_b64 s[18:19], vcc
	global_store_dwordx4 v111, v[64:67], s[12:13] nt
	global_store_dwordx4 v111, v[68:71], s[14:15] nt
	s_mov_b64 exec, s[18:19]
	v_add_u32_e32 v105, 0x8c000, v104
	v_and_b32_e32 v106, 0x1fff, v105
	v_cmp_gt_u32_e32 vcc, 0x1f00, v106
	v_cmp_gt_u32_e64 s[18:19], s21, v105
	s_and_b64 vcc, vcc, s[18:19]
	v_lshlrev_b32_e32 v112, 4, v105
	s_and_saveexec_b64 s[18:19], vcc
	global_store_dwordx4 v112, v[72:75], s[12:13] nt
	global_store_dwordx4 v112, v[76:79], s[14:15] nt
	s_mov_b64 exec, s[18:19]
	v_add_u32_e32 v105, 0x96000, v104
	v_and_b32_e32 v106, 0x1fff, v105
	v_cmp_gt_u32_e32 vcc, 0x1f00, v106
	v_cmp_gt_u32_e64 s[18:19], s21, v105
	s_and_b64 vcc, vcc, s[18:19]
	v_lshlrev_b32_e32 v113, 4, v105
	s_and_saveexec_b64 s[18:19], vcc
	global_store_dwordx4 v113, v[80:83], s[12:13] nt
	global_store_dwordx4 v113, v[84:87], s[14:15] nt
	s_mov_b64 exec, s[18:19]
	v_add_u32_e32 v105, 0xa0000, v104
	v_and_b32_e32 v106, 0x1fff, v105
	v_cmp_gt_u32_e32 vcc, 0x1f00, v106
	v_cmp_gt_u32_e64 s[18:19], s21, v105
	s_and_b64 vcc, vcc, s[18:19]
	v_lshlrev_b32_e32 v114, 4, v105
	s_and_saveexec_b64 s[18:19], vcc
	global_store_dwordx4 v114, v[88:91], s[12:13] nt
	global_store_dwordx4 v114, v[92:95], s[14:15] nt
	s_mov_b64 exec, s[18:19]
	v_add_u32_e32 v105, 0xaa000, v104
	v_and_b32_e32 v106, 0x1fff, v105
	v_cmp_gt_u32_e32 vcc, 0x1f00, v106
	v_cmp_gt_u32_e64 s[18:19], s21, v105
	s_and_b64 vcc, vcc, s[18:19]
	v_lshlrev_b32_e32 v115, 4, v105
	s_and_saveexec_b64 s[18:19], vcc
	global_store_dwordx4 v115, v[96:99], s[12:13] nt
	global_store_dwordx4 v115, v[100:103], s[14:15] nt
	s_mov_b64 exec, s[18:19]
.Lmy_kv_end:
.LBB0_1188:
	s_cmp_gt_i32 s87, 11
	s_cselect_b64 s[0:1], -1, 0
	s_and_b64 s[2:3], s[6:7], s[0:1]
	s_andn2_b64 vcc, exec, s[2:3]
	s_cbranch_vccnz .LBB0_1238
	s_waitcnt vmcnt(0)
	s_waitcnt vmcnt(0)
	s_barrier
	s_mov_b64 s[2:3], exec
	v_readlane_b32 s4, v245, 1
	v_readlane_b32 s5, v245, 2
	s_and_b64 s[4:5], s[2:3], s[4:5]
	s_mov_b64 exec, s[4:5]
	s_cbranch_execz .LBB0_1237
	s_add_i32 s4, 0, 0x23ff0
	v_mov_b32_e32 v0, s4
	s_waitcnt vmcnt(0) expcnt(0) lgkmcnt(0)
	ds_read_b32 v2, v0
	s_add_i32 s4, 0, 0x23ff4
	v_mov_b32_e32 v0, s4
	ds_read_b32 v0, v0
	s_waitcnt lgkmcnt(1)
	v_cmp_ne_u32_e32 vcc, 0, v2
	s_cbranch_vccnz .LBB0_1205
	v_readlane_b32 s4, v245, 0
	s_mul_i32 s46, s89, s4
	s_add_u32 s4, s84, 0x1da00300
	s_addc_u32 s5, s85, 0
	s_add_u32 s6, s84, 0x1da00500
	s_addc_u32 s7, s85, 0
	s_add_u32 s8, s84, 0x1da00600
	s_addc_u32 s9, s85, 0
	s_add_u32 s10, s84, 0x1da00700
	s_addc_u32 s11, s85, 0
	s_add_u32 s12, s84, 0x1da00800
	s_addc_u32 s13, s85, 0
	s_add_u32 s14, s84, 0x1da00900
	s_addc_u32 s15, s85, 0
	s_add_u32 s16, s84, 0x1da00a00
	s_addc_u32 s17, s85, 0
	s_add_u32 s18, s84, 0x1da00b00
	s_addc_u32 s19, s85, 0
	s_add_u32 s20, s84, 0x1da00c00
	s_addc_u32 s21, s85, 0
	s_add_u32 s22, s84, 0x1da00d00
	s_addc_u32 s23, s85, 0
	s_add_u32 s24, s84, 0x1da00e00
	s_addc_u32 s25, s85, 0
	s_add_u32 s26, s84, 0x1da00f00
	s_addc_u32 s27, s85, 0
	s_add_u32 s28, s84, 0x1da01000
	s_addc_u32 s29, s85, 0
	s_add_u32 s30, s84, 0x1da01100
	s_addc_u32 s31, s85, 0
	s_add_u32 s34, s84, 0x1da01200
	s_addc_u32 s35, s85, 0
	s_add_u32 s36, s84, 0x1da01300
	s_addc_u32 s37, s85, 0
	s_add_u32 s38, s84, 0x1da01400
	s_mul_i32 s46, s46, s88
	s_addc_u32 s39, s85, 0
	s_mov_b32 s47, 1
	v_mov_b32_e32 v16, 0
	s_branch .LBB0_1193
